# LDS fragment reads spread one per MFMA gap; QK waits split; A: g3 prefetch + P0 cvt at end of softmax
# speedup vs baseline: 1.0080x; 1.0080x over previous
; DI void diff_core(unsigned char* smem, const u16* qptr, const u16* kbase, const u16* vtbase, int vld,
;                   int ntb, int ntw, int nvalid, int ks0, const float* lut, int qpos, bool active, bool grpB,
;                   f32x16 (&O)[4], float& l_out) {
;     ...
;     float mx = S[0][0];
; #pragma unroll
;     for (int kb = 0; kb < 2; ++kb)
; #pragma unroll
;       for (int i = 0; i < 16; ++i) mx = fmaxf(mx, S[kb][i]);
;     {
;       const unsigned um = __float_as_uint(mx);
;       const auto sw = __builtin_amdgcn_permlane32_swap(um, um, false, false);
;       mx = fmaxf(__uint_as_float(sw[0]), __uint_as_float(sw[1]));
;     }
;     if (t == 0) {
;       m = mx;
; #pragma unroll
;       for (int kb = 0; kb < 2; ++kb)
; #pragma unroll
;         for (int i = 0; i < 16; ++i) S[kb][i] -= mx;
;     } else if (__any(mx > 8.f)) {
;       const float d = fmaxf(mx, 0.f);
;       const float alpha = __builtin_amdgcn_exp2f(-d);
;       m += d;
;       l *= alpha;
; #pragma unroll
;       for (int tt = 0; tt < 4; ++tt)
; #pragma unroll
;         for (int e = 0; e < 16; ++e) O[tt][e] *= alpha;
; #pragma unroll
;       for (int kb = 0; kb < 2; ++kb)
; #pragma unroll
;         for (int i = 0; i < 16; ++i) S[kb][i] -= d;
;     }
;     float ps = 0.f;
; #pragma unroll
;     for (int kb = 0; kb < 2; ++kb)
; #pragma unroll
;       for (int i = 0; i < 16; ++i) {
;         const float pe = __builtin_amdgcn_exp2f(S[kb][i]);
;         S[kb][i] = pe;
;         ps += pe;
;       }
;     l += ps;
; #pragma unroll
;     for (int kb = 0; kb < 2; ++kb)
; #pragma unroll
;       for (int s2 = 0; s2 < 2; ++s2) {
;         u32x4 pk;
;         pk.x = pack2(S[kb][8 * s2 + 0], S[kb][8 * s2 + 1]);
;         pk.y = pack2(S[kb][8 * s2 + 2], S[kb][8 * s2 + 3]);
;         pk.z = pack2(S[kb][8 * s2 + 4], S[kb][8 * s2 + 5]);
;         pk.w = pack2(S[kb][8 * s2 + 6], S[kb][8 * s2 + 7]);
;         P[kb * 2 + s2] = pk;
;       }
.LBB0_357:
	v_max_f32_e32 v32, v1, v1
	v_max_f32_e32 v33, v0, v0
	v_max_f32_e32 v32, v33, v32
	v_max3_f32 v32, v32, v2, v3
	v_max3_f32 v32, v32, v4, v5
	v_max3_f32 v32, v32, v6, v7
	v_max3_f32 v32, v32, v8, v9
	v_max3_f32 v32, v32, v10, v11
	v_max3_f32 v32, v32, v12, v13
	v_max3_f32 v32, v32, v14, v15
	v_max3_f32 v32, v32, v16, v17
	v_max3_f32 v32, v32, v18, v19
	v_max3_f32 v32, v32, v20, v21
	v_max3_f32 v32, v32, v22, v23
	v_max3_f32 v32, v32, v24, v25
	v_max3_f32 v32, v32, v26, v27
	v_max3_f32 v32, v32, v28, v29
	v_max3_f32 v32, v32, v30, v31
	v_mov_b32_e32 v33, v32
	s_nop 1
	v_permlane32_swap_b32_e32 v32, v33
	v_max_f32_e32 v33, v33, v33
	v_max_f32_e32 v32, v32, v32
	v_max_f32_e32 v191, v32, v33
	v_xor_b32_e32 v232, 0x80000000, v191
	v_mov_b32_e32 v233, v232
	v_mov_b32_e32 v234, v232
	v_mov_b32_e32 v235, v232
	v_mov_b32_e32 v236, v232
	v_mov_b32_e32 v237, v232
	v_mov_b32_e32 v238, v232
	v_mov_b32_e32 v239, v232
	v_mov_b32_e32 v240, v232
	v_mov_b32_e32 v241, v232
	v_mov_b32_e32 v242, v232
	v_mov_b32_e32 v243, v232
	v_mov_b32_e32 v244, v232
	v_mov_b32_e32 v245, v232
	v_mov_b32_e32 v246, v232
	v_mov_b32_e32 v247, v232
	v_sub_f32_e32 v0, v0, v191
	v_sub_f32_e32 v1, v1, v191
	v_exp_f32_e32 v96, v0
	v_sub_f32_e32 v2, v2, v191
	v_exp_f32_e32 v97, v1
	v_sub_f32_e32 v3, v3, v191
	v_exp_f32_e32 v98, v2
	v_sub_f32_e32 v4, v4, v191
	v_exp_f32_e32 v99, v3
	v_sub_f32_e32 v5, v5, v191
	v_exp_f32_e32 v100, v4
	v_sub_f32_e32 v6, v6, v191
	v_exp_f32_e32 v101, v5
	v_sub_f32_e32 v7, v7, v191
	v_exp_f32_e32 v102, v6
	v_sub_f32_e32 v8, v8, v191
	v_exp_f32_e32 v103, v7
	v_sub_f32_e32 v9, v9, v191
	v_exp_f32_e32 v104, v8
	v_sub_f32_e32 v10, v10, v191
	v_exp_f32_e32 v105, v9
	v_sub_f32_e32 v11, v11, v191
	v_exp_f32_e32 v106, v10
	v_sub_f32_e32 v12, v12, v191
	v_exp_f32_e32 v107, v11
	v_sub_f32_e32 v13, v13, v191
	v_exp_f32_e32 v108, v12
	v_sub_f32_e32 v14, v14, v191
	v_exp_f32_e32 v109, v13
	v_sub_f32_e32 v15, v15, v191
	v_exp_f32_e32 v110, v14
	v_sub_f32_e32 v16, v16, v191
	v_exp_f32_e32 v111, v15
	v_sub_f32_e32 v17, v17, v191
	v_exp_f32_e32 v112, v16
	v_sub_f32_e32 v18, v18, v191
	v_exp_f32_e32 v113, v17
	v_sub_f32_e32 v19, v19, v191
	v_exp_f32_e32 v114, v18
	v_sub_f32_e32 v20, v20, v191
	v_exp_f32_e32 v115, v19
	v_sub_f32_e32 v21, v21, v191
	v_exp_f32_e32 v116, v20
	v_sub_f32_e32 v22, v22, v191
	v_exp_f32_e32 v117, v21
	v_sub_f32_e32 v23, v23, v191
	v_exp_f32_e32 v118, v22
	v_sub_f32_e32 v24, v24, v191
	v_exp_f32_e32 v119, v23
	v_sub_f32_e32 v25, v25, v191
	v_exp_f32_e32 v120, v24
	v_sub_f32_e32 v26, v26, v191
	v_exp_f32_e32 v121, v25
	v_sub_f32_e32 v27, v27, v191
	v_exp_f32_e32 v122, v26
	v_sub_f32_e32 v28, v28, v191
	v_exp_f32_e32 v123, v27
	v_sub_f32_e32 v29, v29, v191
	v_exp_f32_e32 v124, v28
	v_sub_f32_e32 v30, v30, v191
	v_exp_f32_e32 v125, v29
	v_sub_f32_e32 v31, v31, v191
	v_exp_f32_e32 v126, v30
	v_exp_f32_e32 v127, v31
	s_lshl_b32 s0, s62, 1
	s_sub_i32 s63, 0, s0
	s_lshl_b32 s0, s59, 10
	s_lshl_b32 s1, s62, 9
	s_add_i32 s0, s0, s1
	v_mov_b32_e32 v181, 0
	v_or_b32_e32 v0, s0, v183
	v_lshlrev_b32_e32 v1, 2, v182
	v_sub_u32_e32 v0, v0, v1
	s_lshl_b32 s0, s39, 7
	v_subrev_u32_e32 v0, s0, v0
	v_mov_b32_e32 v14, v163
	v_mov_b32_e32 v15, v163
	v_add_u32_e32 v199, s38, v0
	v_mov_b32_e32 v0, v163
	v_mov_b32_e32 v1, v163
	v_mov_b32_e32 v2, v163
	v_mov_b32_e32 v3, v163
	v_mov_b32_e32 v4, v163
	v_mov_b32_e32 v5, v163
	v_mov_b32_e32 v6, v163
	v_mov_b32_e32 v7, v163
	v_mov_b32_e32 v8, v163
	v_mov_b32_e32 v9, v163
	v_mov_b32_e32 v10, v163
	v_mov_b32_e32 v11, v163
	v_mov_b32_e32 v12, v163
	v_mov_b32_e32 v13, v163
	v_mov_b64_e32 v[30:31], v[14:15]
	v_mov_b64_e32 v[46:47], v[14:15]
	v_mov_b64_e32 v[62:63], v[14:15]
	v_add_u32_e32 v195, v188, v184
	v_add_u32_e32 v196, v187, v184
	v_add_u32_e32 v197, v186, v184
	v_add_u32_e32 v198, v185, v184
	s_movk_i32 s64, 0xff00
	s_mov_b32 s65, 0x20000
	v_mov_b64_e32 v[28:29], v[12:13]
	v_mov_b64_e32 v[26:27], v[10:11]
	v_mov_b64_e32 v[24:25], v[8:9]
	v_mov_b64_e32 v[22:23], v[6:7]
	v_mov_b64_e32 v[20:21], v[4:5]
	v_mov_b64_e32 v[18:19], v[2:3]
	v_mov_b64_e32 v[16:17], v[0:1]
	v_mov_b64_e32 v[44:45], v[12:13]
	v_mov_b64_e32 v[42:43], v[10:11]
	v_mov_b64_e32 v[40:41], v[8:9]
	v_mov_b64_e32 v[38:39], v[6:7]
	v_mov_b64_e32 v[36:37], v[4:5]
	v_mov_b64_e32 v[34:35], v[2:3]
	v_mov_b64_e32 v[32:33], v[0:1]
	v_mov_b64_e32 v[60:61], v[12:13]
	v_mov_b64_e32 v[58:59], v[10:11]
	v_mov_b64_e32 v[56:57], v[8:9]
	v_mov_b64_e32 v[54:55], v[6:7]
	v_mov_b64_e32 v[52:53], v[4:5]
	v_mov_b64_e32 v[50:51], v[2:3]
	v_mov_b64_e32 v[48:49], v[0:1]
	s_mov_b32 s0, 0
	v_add_u32_e32 v248, s0, v195
	ds_read_b128 v[200:203], v248 offset:16384
	ds_read_b128 v[204:207], v248 offset:20480
	ds_read_b128 v[208:211], v248 offset:24576
	ds_read_b128 v[212:215], v248 offset:28672
	v_add_u32_e32 v249, s0, v196
	ds_read_b128 v[216:219], v249 offset:16384
	ds_read_b128 v[220:223], v249 offset:20480
	ds_read_b128 v[224:227], v249 offset:24576
	ds_read_b128 v[228:231], v249 offset:28672
	v_add_u32_e32 v248, s0, v197
	ds_read_b128 v[64:67], v248 offset:16384
	ds_read_b128 v[68:71], v248 offset:20480
	ds_read_b128 v[72:75], v248 offset:24576
	ds_read_b128 v[76:79], v248 offset:28672
	v_cvt_pk_bf16_f32 v144, v96, v97
	v_cvt_pk_bf16_f32 v145, v98, v99
	v_cvt_pk_bf16_f32 v146, v100, v101
	v_cvt_pk_bf16_f32 v147, v102, v103
	v_add_f32_e32 v250, v97, v96
	v_add_f32_e32 v250, v98, v250
	s_branch .LBB0_360
; #define LAS __attribute__((address_space(3)))
; DI void diff_core(unsigned char* smem, const u16* qptr, const u16* kbase, const u16* vtbase, int vld,
;                   int ntb, int ntw, int nvalid, int ks0, const float* lut, int qpos, bool active, bool grpB,
;                   f32x16 (&O)[4], float& l_out) {
;     ...
;   auto pv = [&](int slot) {
;     if (grpB) __builtin_amdgcn_s_setprio(2); else __builtin_amdgcn_s_setprio(1);
;     const LAS unsigned char* b = lds + slot * D_SLOT;
;     bf16x8 va[4], vb[4];
; #pragma unroll
;     for (int tt = 0; tt < 4; ++tt) va[tt] = *reinterpret_cast<const LAS bf16x8*>(b + voff[0] + tt * 32 * 128);
; #pragma unroll
;     for (int tt = 0; tt < 4; ++tt) vb[tt] = *reinterpret_cast<const LAS bf16x8*>(b + voff[1] + tt * 32 * 128);
;     ...
;     float ps = 0.f;
; #pragma unroll
;     for (int kb = 0; kb < 2; ++kb)
; #pragma unroll
;       for (int i = 0; i < 16; ++i) {
;         const float pe = __builtin_amdgcn_exp2f(S[kb][i]);
;         S[kb][i] = pe;
;         ps += pe;
;       }
;     l += ps;
; #pragma unroll
;     for (int kb = 0; kb < 2; ++kb)
; #pragma unroll
;       for (int s2 = 0; s2 < 2; ++s2) {
;         u32x4 pk;
;         pk.x = pack2(S[kb][8 * s2 + 0], S[kb][8 * s2 + 1]);
;         pk.y = pack2(S[kb][8 * s2 + 2], S[kb][8 * s2 + 3]);
;         pk.z = pack2(S[kb][8 * s2 + 4], S[kb][8 * s2 + 5]);
;         pk.w = pack2(S[kb][8 * s2 + 6], S[kb][8 * s2 + 7]);
;         P[kb * 2 + s2] = pk;
;       }
.LBB0_358:
	v_exp_f32_e32 v96, v96
	v_exp_f32_e32 v97, v97
	v_exp_f32_e32 v98, v98
	v_exp_f32_e32 v99, v99
	v_exp_f32_e32 v100, v100
	v_exp_f32_e32 v101, v101
	v_exp_f32_e32 v102, v102
	v_exp_f32_e32 v103, v103
	v_exp_f32_e32 v104, v104
	v_exp_f32_e32 v105, v105
	v_exp_f32_e32 v106, v106
	v_exp_f32_e32 v107, v107
	v_exp_f32_e32 v108, v108
	v_exp_f32_e32 v109, v109
	v_exp_f32_e32 v110, v110
	v_exp_f32_e32 v111, v111
	v_exp_f32_e32 v112, v112
	v_exp_f32_e32 v113, v113
	v_exp_f32_e32 v114, v114
	v_exp_f32_e32 v115, v115
	v_exp_f32_e32 v116, v116
	v_exp_f32_e32 v117, v117
	v_exp_f32_e32 v118, v118
	v_exp_f32_e32 v119, v119
	v_exp_f32_e32 v120, v120
	v_exp_f32_e32 v121, v121
	v_exp_f32_e32 v122, v122
	v_exp_f32_e32 v123, v123
	v_exp_f32_e32 v124, v124
	v_exp_f32_e32 v125, v125
	v_exp_f32_e32 v126, v126
	v_exp_f32_e32 v127, v127
	s_add_i32 s0, s65, 0x8000
	s_and_b32 s0, s0, 0x18000
	v_add_u32_e32 v248, s0, v195
	ds_read_b128 v[200:203], v248 offset:16384
	ds_read_b128 v[204:207], v248 offset:20480
	ds_read_b128 v[208:211], v248 offset:24576
	ds_read_b128 v[212:215], v248 offset:28672
	v_add_u32_e32 v249, s0, v196
	ds_read_b128 v[216:219], v249 offset:16384
	ds_read_b128 v[220:223], v249 offset:20480
	ds_read_b128 v[224:227], v249 offset:24576
	ds_read_b128 v[228:231], v249 offset:28672
	v_add_u32_e32 v248, s0, v197
	ds_read_b128 v[64:67], v248 offset:16384
	ds_read_b128 v[68:71], v248 offset:20480
	ds_read_b128 v[72:75], v248 offset:24576
	ds_read_b128 v[76:79], v248 offset:28672
	v_cvt_pk_bf16_f32 v144, v96, v97
	v_cvt_pk_bf16_f32 v145, v98, v99
	v_cvt_pk_bf16_f32 v146, v100, v101
	v_cvt_pk_bf16_f32 v147, v102, v103
	v_add_f32_e32 v250, v97, v96
	v_add_f32_e32 v250, v98, v250

; DI void diff_core(unsigned char* smem, const u16* qptr, const u16* kbase, const u16* vtbase, int vld,
;                   int ntb, int ntw, int nvalid, int ks0, const float* lut, int qpos, bool active, bool grpB,
;                   f32x16 (&O)[4], float& l_out) {
;     ...
;   auto qk = [&](int slot) {
;     if (grpB) __builtin_amdgcn_s_setprio(2); else __builtin_amdgcn_s_setprio(1);
;     const float ini = -m;
; #pragma unroll
;     for (int kb = 0; kb < 2; ++kb)
; #pragma unroll
;       for (int e = 0; e < 16; ++e) S[kb][e] = ini;
;     const LAS unsigned char* b = lds + slot * D_SLOT;
;     bf16x8 kf[4][2];
; #pragma unroll
;     ...
;   auto pv = [&](int slot) {
;     if (grpB) __builtin_amdgcn_s_setprio(2); else __builtin_amdgcn_s_setprio(1);
;     const LAS unsigned char* b = lds + slot * D_SLOT;
;     bf16x8 va[4], vb[4];
; #pragma unroll
;     for (int tt = 0; tt < 4; ++tt) va[tt] = *reinterpret_cast<const LAS bf16x8*>(b + voff[0] + tt * 32 * 128);
; #pragma unroll
;     for (int tt = 0; tt < 4; ++tt) vb[tt] = *reinterpret_cast<const LAS bf16x8*>(b + voff[1] + tt * 32 * 128);
;     {
;       const bf16x8 pf = __builtin_bit_cast(bf16x8, P[0]);
; #pragma unroll
;       for (int tt = 0; tt < 4; ++tt) O[tt] = MFMA(va[tt], pf, O[tt]);
;     }
; #pragma unroll
;     for (int tt = 0; tt < 4; ++tt) va[tt] = *reinterpret_cast<const LAS bf16x8*>(b + voff[2] + tt * 32 * 128);
;     {
;       const bf16x8 pf = __builtin_bit_cast(bf16x8, P[1]);
; #pragma unroll
;       for (int tt = 0; tt < 4; ++tt) O[tt] = MFMA(vb[tt], pf, O[tt]);
;     }
; #pragma unroll
;     for (int tt = 0; tt < 4; ++tt) vb[tt] = *reinterpret_cast<const LAS bf16x8*>(b + voff[3] + tt * 32 * 128);
;     {
;       const bf16x8 pf = __builtin_bit_cast(bf16x8, P[2]);
; #pragma unroll
;       for (int tt = 0; tt < 4; ++tt) O[tt] = MFMA(va[tt], pf, O[tt]);
;     }
;     {
;       const bf16x8 pf = __builtin_bit_cast(bf16x8, P[3]);
; #pragma unroll
;       for (int tt = 0; tt < 4; ++tt) O[tt] = MFMA(vb[tt], pf, O[tt]);
;     }
;     __builtin_amdgcn_sched_group_barrier(0x100, 8, 0);
;     __builtin_amdgcn_sched_group_barrier(0x008, 4, 0);
;     __builtin_amdgcn_sched_group_barrier(0x100, 4, 0);
;     __builtin_amdgcn_sched_group_barrier(0x008, 4, 0);
;     __builtin_amdgcn_sched_group_barrier(0x100, 4, 0);
;     __builtin_amdgcn_sched_group_barrier(0x008, 8, 0);
;     __builtin_amdgcn_s_setprio(0);
;   };
.LBB0_360:
	s_add_i32 s66, s64, 0x101
	s_cmp_gt_u32 s66, s16
	s_cbranch_scc1 .LBB0_362
	s_setprio 1
	s_and_b32 s0, s65, 0x18000
	s_add_i32 s67, s65, 0xfffe8000
	s_and_b32 s67, s67, 0x18000
	s_waitcnt lgkmcnt(8)
	v_mfma_f32_32x32x16_bf16 v[48:63], v[200:203], v[144:147], v[48:63]
	v_cvt_pk_bf16_f32 v148, v104, v105
	v_add_f32_e32 v250, v99, v250
	v_add_f32_e32 v250, v100, v250
	v_add_u32_e32 v249, s0, v198
	ds_read_b128 v[80:83], v249 offset:16384
	v_mfma_f32_32x32x16_bf16 v[32:47], v[204:207], v[144:147], v[32:47]
	v_cvt_pk_bf16_f32 v149, v106, v107
	v_add_f32_e32 v250, v101, v250
	v_add_f32_e32 v250, v102, v250
	ds_read_b128 v[84:87], v249 offset:20480
	v_mfma_f32_32x32x16_bf16 v[16:31], v[208:211], v[144:147], v[16:31]
	v_cvt_pk_bf16_f32 v150, v108, v109
	v_add_f32_e32 v250, v103, v250
	v_add_f32_e32 v250, v104, v250
	ds_read_b128 v[88:91], v249 offset:24576
	v_mfma_f32_32x32x16_bf16 v[0:15], v[212:215], v[144:147], v[0:15]
	v_cvt_pk_bf16_f32 v151, v110, v111
	v_add_f32_e32 v250, v105, v250
	v_add_f32_e32 v250, v106, v250
	ds_read_b128 v[92:95], v249 offset:28672
	s_waitcnt lgkmcnt(8)
	v_mfma_f32_32x32x16_bf16 v[48:63], v[216:219], v[148:151], v[48:63]
	v_cvt_pk_bf16_f32 v152, v112, v113
	v_add_f32_e32 v250, v107, v250
	v_add_f32_e32 v250, v108, v250
	v_add_u32_e32 v248, s67, v177
	ds_read_b128 v[200:203], v248
	v_mfma_f32_32x32x16_bf16 v[32:47], v[220:223], v[148:151], v[32:47]
	v_cvt_pk_bf16_f32 v153, v114, v115
	v_add_f32_e32 v250, v109, v250
	v_add_f32_e32 v250, v110, v250
	ds_read_b128 v[204:207], v248 offset:8192
	v_mfma_f32_32x32x16_bf16 v[16:31], v[224:227], v[148:151], v[16:31]
	v_cvt_pk_bf16_f32 v154, v116, v117
	v_add_f32_e32 v250, v111, v250
	v_add_f32_e32 v250, v112, v250
	v_add_u32_e32 v249, s67, v178
	ds_read_b128 v[208:211], v249
	v_mfma_f32_32x32x16_bf16 v[0:15], v[228:231], v[148:151], v[0:15]
	v_cvt_pk_bf16_f32 v155, v118, v119
	v_add_f32_e32 v250, v113, v250
	v_add_f32_e32 v250, v114, v250
	ds_read_b128 v[212:215], v249 offset:8192
	s_waitcnt lgkmcnt(8)
	v_mfma_f32_32x32x16_bf16 v[48:63], v[64:67], v[152:155], v[48:63]
	v_cvt_pk_bf16_f32 v156, v120, v121
	v_add_f32_e32 v250, v115, v250
	v_add_f32_e32 v250, v116, v250
	v_add_u32_e32 v248, s67, v179
	ds_read_b128 v[216:219], v248
	v_mfma_f32_32x32x16_bf16 v[32:47], v[68:71], v[152:155], v[32:47]
	v_cvt_pk_bf16_f32 v157, v122, v123
	v_add_f32_e32 v250, v117, v250
	v_add_f32_e32 v250, v118, v250
	ds_read_b128 v[220:223], v248 offset:8192
	v_mfma_f32_32x32x16_bf16 v[16:31], v[72:75], v[152:155], v[16:31]
	v_cvt_pk_bf16_f32 v158, v124, v125
	v_add_f32_e32 v250, v119, v250
	v_add_f32_e32 v250, v120, v250
	v_add_u32_e32 v249, s67, v180
	ds_read_b128 v[224:227], v249
	v_mfma_f32_32x32x16_bf16 v[0:15], v[76:79], v[152:155], v[0:15]
	v_cvt_pk_bf16_f32 v159, v126, v127
	v_add_f32_e32 v250, v121, v250
	v_add_f32_e32 v250, v122, v250
	ds_read_b128 v[228:231], v249 offset:8192
	s_waitcnt lgkmcnt(8)
	v_mfma_f32_32x32x16_bf16 v[48:63], v[80:83], v[156:159], v[48:63]
	v_add_f32_e32 v250, v123, v250
	v_add_f32_e32 v250, v124, v250
	v_mfma_f32_32x32x16_bf16 v[32:47], v[84:87], v[156:159], v[32:47]
	v_add_f32_e32 v250, v125, v250
	v_add_f32_e32 v250, v126, v250
	v_mfma_f32_32x32x16_bf16 v[16:31], v[88:91], v[156:159], v[16:31]
	v_add_f32_e32 v250, v127, v250
	v_mfma_f32_32x32x16_bf16 v[0:15], v[92:95], v[156:159], v[0:15]
	v_add_f32_e32 v181, v181, v250
	s_setprio 0
.LBB0_362:
	s_cmp_lt_u32 s66, s16
	s_cselect_b64 s[0:1], -1, 0
	s_cmp_ge_u32 s66, s16
	s_cbranch_scc1 .LBB0_364
	s_setprio 1
	s_waitcnt lgkmcnt(4)
	v_mfma_f32_32x32x16_bf16 v[96:111], v[200:203], v[128:131], v[232:247]
	v_mfma_f32_32x32x16_bf16 v[112:127], v[204:207], v[128:131], v[232:247]
	v_mfma_f32_32x32x16_bf16 v[96:111], v[208:211], v[132:135], v[96:111]
	v_mfma_f32_32x32x16_bf16 v[112:127], v[212:215], v[132:135], v[112:127]
	s_waitcnt lgkmcnt(0)
	v_mfma_f32_32x32x16_bf16 v[96:111], v[216:219], v[136:139], v[96:111]
	v_mfma_f32_32x32x16_bf16 v[112:127], v[220:223], v[136:139], v[112:127]
	v_mfma_f32_32x32x16_bf16 v[96:111], v[224:227], v[140:143], v[96:111]
	v_mfma_f32_32x32x16_bf16 v[112:127], v[228:231], v[140:143], v[112:127]
	s_setprio 0

; DI void diff_core(unsigned char* smem, const u16* qptr, const u16* kbase, const u16* vtbase, int vld,
;                   int ntb, int ntw, int nvalid, int ks0, const float* lut, int qpos, bool active, bool grpB,
;                   f32x16 (&O)[4], float& l_out) {
;     ...
;   auto pv = [&](int slot) {
;     if (grpB) __builtin_amdgcn_s_setprio(2); else __builtin_amdgcn_s_setprio(1);
;     const LAS unsigned char* b = lds + slot * D_SLOT;
;     bf16x8 va[4], vb[4];
; #pragma unroll
;     for (int tt = 0; tt < 4; ++tt) va[tt] = *reinterpret_cast<const LAS bf16x8*>(b + voff[0] + tt * 32 * 128);
; #pragma unroll
;     for (int tt = 0; tt < 4; ++tt) vb[tt] = *reinterpret_cast<const LAS bf16x8*>(b + voff[1] + tt * 32 * 128);
;     {
;       const bf16x8 pf = __builtin_bit_cast(bf16x8, P[0]);
; #pragma unroll
;       for (int tt = 0; tt < 4; ++tt) O[tt] = MFMA(va[tt], pf, O[tt]);
;     }
; #pragma unroll
;     for (int tt = 0; tt < 4; ++tt) va[tt] = *reinterpret_cast<const LAS bf16x8*>(b + voff[2] + tt * 32 * 128);
;     {
;       const bf16x8 pf = __builtin_bit_cast(bf16x8, P[1]);
; #pragma unroll
;       for (int tt = 0; tt < 4; ++tt) O[tt] = MFMA(vb[tt], pf, O[tt]);
;     }
; #pragma unroll
;     for (int tt = 0; tt < 4; ++tt) vb[tt] = *reinterpret_cast<const LAS bf16x8*>(b + voff[3] + tt * 32 * 128);
;     {
;       const bf16x8 pf = __builtin_bit_cast(bf16x8, P[2]);
; #pragma unroll
;       for (int tt = 0; tt < 4; ++tt) O[tt] = MFMA(va[tt], pf, O[tt]);
;     }
;     {
;       const bf16x8 pf = __builtin_bit_cast(bf16x8, P[3]);
; #pragma unroll
;       for (int tt = 0; tt < 4; ++tt) O[tt] = MFMA(vb[tt], pf, O[tt]);
;     }
;     __builtin_amdgcn_sched_group_barrier(0x100, 8, 0);
;     __builtin_amdgcn_sched_group_barrier(0x008, 4, 0);
;     __builtin_amdgcn_sched_group_barrier(0x100, 4, 0);
;     __builtin_amdgcn_sched_group_barrier(0x008, 4, 0);
;     __builtin_amdgcn_sched_group_barrier(0x100, 4, 0);
;     __builtin_amdgcn_sched_group_barrier(0x008, 8, 0);
;     ...
;     for (int t = 0; t <= ntb; ++t) {
;       const bool act_t = active && (t < ntw);
;       { const int tn = t + 2; dma(tn < tlast ? tn : tlast, tn & 3); }
;       if (act_t) softmax(t);
;       asm volatile("s_waitcnt vmcnt(4)" ::: "memory");
;       D_BAR;
;       if (act_t) pv(t & 3);
;       __builtin_amdgcn_sched_barrier(0);
;       if (active && (t + 1) < ntw) qk((t + 1) & 3);
.LBB0_384:
	s_waitcnt vmcnt(4)
	s_barrier
	s_andn2_b64 vcc, exec, s[0:1]
	s_cbranch_vccnz .LB_dma_only
	s_setprio 2
	s_add_i32 s0, s59, 0xffff0000
	s_and_b32 s0, s0, 0x18000
	s_add_i32 s101, s59, 0xffff8000
	s_and_b32 s101, s101, 0x18000
	v_add_u32_e32 v97, s0, v186
	ds_read_b128 v[98:101], v97 offset:16384
	ds_read_b128 v[102:105], v97 offset:20480
	ds_read_b128 v[106:109], v97 offset:24576
	ds_read_b128 v[110:113], v97 offset:28672
	s_waitcnt lgkmcnt(8)
	s_mov_b32 m0, s85
	v_mfma_f32_32x32x16_bf16 v[48:63], v[200:203], v[144:147], v[48:63]
	v_cvt_pk_bf16_f32 v148, v88, v89
	v_add_f32_e32 v250, v83, v250
	v_add_f32_e32 v250, v84, v250
	global_load_lds_dwordx4 v162, s[86:87]
	v_add_u32_e32 v126, s0, v184
	ds_read_b128 v[114:117], v126 offset:16384
	s_mov_b32 m0, s65
	v_mfma_f32_32x32x16_bf16 v[32:47], v[204:207], v[144:147], v[32:47]
	v_cvt_pk_bf16_f32 v149, v90, v91
	v_add_f32_e32 v250, v85, v250
	v_add_f32_e32 v250, v86, v250
	global_load_lds_dwordx4 v170, s[86:87]
	ds_read_b128 v[118:121], v126 offset:20480
	s_mov_b32 m0, s88
	v_mfma_f32_32x32x16_bf16 v[16:31], v[208:211], v[144:147], v[16:31]
	v_cvt_pk_bf16_f32 v150, v92, v93
	v_add_f32_e32 v250, v87, v250
	v_add_f32_e32 v250, v88, v250
	global_load_lds_dwordx4 v166, s[66:67]
	ds_read_b128 v[122:125], v126 offset:24576
	s_mov_b32 m0, s89
	v_mfma_f32_32x32x16_bf16 v[0:15], v[212:215], v[144:147], v[0:15]
	v_cvt_pk_bf16_f32 v151, v94, v95
	v_add_f32_e32 v250, v89, v250
	v_add_f32_e32 v250, v90, v250
	global_load_lds_dwordx4 v168, s[66:67]
	ds_read_b128 v[196:199], v126 offset:28672
	s_waitcnt lgkmcnt(8)
	v_mfma_f32_32x32x16_bf16 v[48:63], v[216:219], v[148:151], v[48:63]
	v_cvt_pk_bf16_f32 v152, v64, v65
	v_add_f32_e32 v250, v91, v250
	v_add_f32_e32 v250, v92, v250
	v_add_u32_e32 v97, s101, v177
	ds_read_b128 v[200:203], v97
	v_mfma_f32_32x32x16_bf16 v[32:47], v[220:223], v[148:151], v[32:47]
	v_cvt_pk_bf16_f32 v153, v66, v67
	v_add_f32_e32 v250, v93, v250
	v_add_f32_e32 v250, v94, v250
	ds_read_b128 v[204:207], v97 offset:8192
	v_mfma_f32_32x32x16_bf16 v[16:31], v[224:227], v[148:151], v[16:31]
	v_cvt_pk_bf16_f32 v154, v68, v69
	v_add_f32_e32 v250, v95, v250
	v_add_f32_e32 v250, v64, v250
	v_add_u32_e32 v126, s101, v178
	ds_read_b128 v[208:211], v126
	v_mfma_f32_32x32x16_bf16 v[0:15], v[228:231], v[148:151], v[0:15]
	v_cvt_pk_bf16_f32 v155, v70, v71
	v_add_f32_e32 v250, v65, v250
	v_add_f32_e32 v250, v66, v250
	ds_read_b128 v[212:215], v126 offset:8192
	s_waitcnt lgkmcnt(8)
	v_mfma_f32_32x32x16_bf16 v[48:63], v[98:101], v[152:155], v[48:63]
	v_cvt_pk_bf16_f32 v156, v72, v73
	v_add_f32_e32 v250, v67, v250
	v_add_f32_e32 v250, v68, v250
	v_add_u32_e32 v97, s101, v179
	ds_read_b128 v[216:219], v97
	v_mfma_f32_32x32x16_bf16 v[32:47], v[102:105], v[152:155], v[32:47]
	v_cvt_pk_bf16_f32 v157, v74, v75
	v_add_f32_e32 v250, v69, v250
	v_add_f32_e32 v250, v70, v250
	ds_read_b128 v[220:223], v97 offset:8192
	v_mfma_f32_32x32x16_bf16 v[16:31], v[106:109], v[152:155], v[16:31]
	v_cvt_pk_bf16_f32 v158, v76, v77
	v_add_f32_e32 v250, v71, v250
	v_add_f32_e32 v250, v72, v250
	v_add_u32_e32 v126, s101, v180
	ds_read_b128 v[224:227], v126
	v_mfma_f32_32x32x16_bf16 v[0:15], v[110:113], v[152:155], v[0:15]
	v_cvt_pk_bf16_f32 v159, v78, v79
	v_add_f32_e32 v250, v73, v250
	v_add_f32_e32 v250, v74, v250
	ds_read_b128 v[228:231], v126 offset:8192
	s_waitcnt lgkmcnt(8)
	v_mfma_f32_32x32x16_bf16 v[48:63], v[114:117], v[156:159], v[48:63]
	v_add_f32_e32 v250, v75, v250
	v_add_f32_e32 v250, v76, v250
	v_mfma_f32_32x32x16_bf16 v[32:47], v[118:121], v[156:159], v[32:47]
	v_add_f32_e32 v250, v77, v250
	v_add_f32_e32 v250, v78, v250
	v_mfma_f32_32x32x16_bf16 v[16:31], v[122:125], v[156:159], v[16:31]
	v_add_f32_e32 v250, v79, v250
	v_mfma_f32_32x32x16_bf16 v[0:15], v[196:199], v[156:159], v[0:15]
	v_add_f32_e32 v181, v181, v250
	s_setprio 0
.LBB0_386:
	s_add_i32 s0, s62, 0x102
	s_cmp_ge_u32 s0, s16
	s_cbranch_scc1 .LBB0_377
	s_setprio 2
	s_waitcnt lgkmcnt(4)
	v_mfma_f32_32x32x16_bf16 v[80:95], v[200:203], v[128:131], v[232:247]
	v_mfma_f32_32x32x16_bf16 v[64:79], v[204:207], v[128:131], v[232:247]
	v_mfma_f32_32x32x16_bf16 v[80:95], v[208:211], v[132:135], v[80:95]
	v_mfma_f32_32x32x16_bf16 v[64:79], v[212:215], v[132:135], v[64:79]
	s_waitcnt lgkmcnt(0)
	v_mfma_f32_32x32x16_bf16 v[80:95], v[216:219], v[136:139], v[80:95]
	v_mfma_f32_32x32x16_bf16 v[64:79], v[220:223], v[136:139], v[64:79]
	v_mfma_f32_32x32x16_bf16 v[80:95], v[224:227], v[140:143], v[80:95]
	v_mfma_f32_32x32x16_bf16 v[64:79], v[228:231], v[140:143], v[64:79]
	s_setprio 0
	s_branch .LBB0_377
